# P9: window tasks drawn through a per-workgroup LDS cursor (6 heads of one tile+group together, L1 reuse); cmp tasks grouped per workgroup; partner wave also takes half of pass-2 steps; P10 top-k row p
# speedup vs baseline: 1.0388x; 1.0367x over previous
.LBB0_1065:
	s_or_b64 exec, exec, s[4:5]
	v_readfirstlane_b32 s4, v5
	s_cmpk_lg_i32 s33, 0x100
	s_cbranch_scc1 .Lp9_keep_idx
	s_lshr_b32 s4, s80, 1
	s_lshl_b32 s4, s4, 2
	s_add_i32 s4, s4, s77
	s_lshl_b32 s4, s4, 1
	s_and_b32 s5, s80, 1
	s_or_b32 s4, s4, s5
.Lp9_keep_idx:
	s_and_saveexec_b64 s[0:1], vcc
	s_cbranch_execz .LBB0_1067
	s_lshl_b32 s5, s77, 2
	s_add_i32 s5, s5, 0
	s_add_i32 s5, s5, 0x1d4c0
	s_add_i32 s7, s4, 1
	s_cmpk_lt_u32 s4, 0x1c0
	s_cselect_b32 s6, s7, 0
	v_mov_b32_e32 v5, s6
	v_mov_b32_e32 v6, s5
	v_mov_b32_e32 v7, 0
	ds_write_b32 v6, v5
	ds_write_b32 v6, v7 offset:32
	ds_write_b32 v6, v7 offset:48
	v_mov_b32_e32 v5, 0x1d500
	v_mov_b32_e32 v7, 6
	ds_write_b32 v5, v7

.LBB0_1097:
	s_cmp_eq_u32 s98, 0
	s_cbranch_scc1 .Lp9_pass2
	s_waitcnt lgkmcnt(0)
	s_lshl_b32 s0, s77, 2
	v_mov_b32_e32 v3, 1
	s_cmp_eq_u32 s101, 0
	s_cbranch_scc1 .Lp9_owner_hs
	s_add_i32 s1, s0, 0x1d4d0
	s_add_i32 s0, s0, 0x1d4e0
	s_branch .Lp9_hs
.Lp9_owner_hs:
	s_add_i32 s1, s0, 0x1d4f0
	s_add_i32 s0, s0, 0x1d4e0
.Lp9_hs:
	v_mov_b32_e32 v2, s1
	ds_write_b32 v2, v3
	v_mov_b32_e32 v2, s0

.Lp9_pass2:
	s_waitcnt lgkmcnt(0)
	global_load_dwordx4 v[2:5], v[184:185], off offset:384
	global_load_dwordx4 v[6:9], v[184:185], off offset:416
	global_load_dwordx4 v[10:13], v[184:185], off offset:448
	global_load_dwordx4 v[14:17], v[184:185], off offset:480
	global_load_dwordx4 v[66:69], v[184:185], off offset:512
	global_load_dwordx4 v[70:73], v[184:185], off offset:544
	global_load_dwordx4 v[74:77], v[184:185], off offset:576
	global_load_dwordx4 v[78:81], v[184:185], off offset:608
	global_load_dwordx4 v[82:85], v[184:185], off offset:640
	global_load_dwordx4 v[86:89], v[184:185], off offset:672
	global_load_dwordx4 v[90:93], v[184:185], off offset:704
	global_load_dwordx4 v[94:97], v[184:185], off offset:736
	ds_read2_b32 v[100:101], v167 offset1:32
	ds_read2_b32 v[102:103], v167 offset0:64 offset1:96
	ds_read2_b32 v[104:105], v167 offset0:128 offset1:160
	global_load_dwordx4 v[18:21], v[184:185], off
	global_load_dwordx4 v[22:25], v[184:185], off offset:32
	global_load_dwordx4 v[26:29], v[184:185], off offset:64
	global_load_dwordx4 v[30:33], v[184:185], off offset:96
	global_load_dwordx4 v[34:37], v[184:185], off offset:128
	global_load_dwordx4 v[38:41], v[184:185], off offset:160
	global_load_dwordx4 v[42:45], v[184:185], off offset:192
	global_load_dwordx4 v[46:49], v[184:185], off offset:224
	global_load_dwordx4 v[50:53], v[184:185], off offset:256
	global_load_dwordx4 v[54:57], v[184:185], off offset:288
	global_load_dwordx4 v[58:61], v[184:185], off offset:320
	global_load_dwordx4 v[62:65], v[184:185], off offset:352
	s_mul_i32 s0, s77, 0x2c00
	s_add_i32 s0, s12, s0
	s_lshl_b32 s4, s101, 12
	s_add_i32 s0, s0, s4
	v_lshl_add_u32 v126, v199, 4, s0
	s_waitcnt lgkmcnt(2)
	v_cmp_lt_f32_e32 vcc, 0, v100
	v_mov_b32_e32 v167, 0
	s_mov_b32 s55, 0
	s_lshl_b32 s54, s8, 10
	s_mov_b64 s[0:1], 0xba00000
	v_or_b32_e32 v98, 1, v1
	v_cmp_gt_u32_e64 s[2:3], 32, v199
	v_mov_b32_e32 v99, v164
	s_mov_b32 s43, 0
	s_mov_b32 s56, s55
	s_mov_b32 s48, 0
	s_mov_b32 s99, s13
	s_mov_b32 s100, 0
	s_cmp_eq_u32 s98, 0
	s_cbranch_scc1 .Lp9_p2_ranges
	s_add_i32 s4, s13, 1
	s_lshr_b32 s4, s4, 1
	s_cmp_eq_u32 s101, 0
	s_cbranch_scc0 .Lp9_p2_partner
	s_mov_b32 s99, s4
	s_branch .Lp9_p2_ranges
.Lp9_p2_partner:
	s_add_i32 s48, s4, -1
	s_mov_b32 s100, s4
	s_lshl_b32 s43, s48, 5
	s_lshl_b32 s56, s48, 3
	s_lshl_b32 s4, s48, 12
	s_mov_b32 s5, 0
	v_lshl_add_u64 v[182:183], v[182:183], 0, s[4:5]
.Lp9_p2_ranges:
	s_waitcnt vmcnt(23)
	ds_write_b128 v126, v[2:5] offset:16384
	s_waitcnt vmcnt(22)
	ds_write_b128 v126, v[6:9] offset:17408
	s_waitcnt vmcnt(21)
	ds_write_b128 v126, v[10:13] offset:18432
	s_waitcnt vmcnt(20)
	ds_write_b128 v126, v[14:17] offset:19456
	s_waitcnt vmcnt(19)
	ds_write_b128 v126, v[66:69] offset:20480
	s_waitcnt vmcnt(18)
	ds_write_b128 v126, v[70:73] offset:21504
	s_waitcnt vmcnt(17)
	ds_write_b128 v126, v[74:77] offset:22528
	s_waitcnt vmcnt(16)
	ds_write_b128 v126, v[78:81] offset:23552
	s_waitcnt vmcnt(15)
	ds_write_b128 v126, v[82:85] offset:24576
	s_waitcnt vmcnt(14)
	ds_write_b128 v126, v[86:89] offset:25600
	s_waitcnt vmcnt(13)
	ds_write_b128 v126, v[90:93] offset:26624
	s_waitcnt vmcnt(12)
	ds_write_b128 v126, v[94:97] offset:27648
	s_waitcnt lgkmcnt(0)
	global_load_dwordx4 v[82:85], v[182:183], off offset:3072
	global_load_dwordx4 v[86:89], v[182:183], off offset:2048
	global_load_dwordx4 v[90:93], v[182:183], off offset:1024
	global_load_dwordx4 v[94:97], v[182:183], off
	v_log_f32_e32 v4, v100
	v_log_f32_e32 v5, v101
	v_mov_b32_e32 v6, 0xf149f2ca
	v_lshlrev_b64 v[2:3], 11, v[166:167]
	v_sub_f32_e32 v4, v4, v224
	v_cndmask_b32_e32 v127, v6, v4, vcc
	v_sub_f32_e32 v4, v5, v224
	s_waitcnt lgkmcnt(13)
	v_log_f32_e32 v5, v102
	v_cmp_lt_f32_e32 vcc, 0, v101
	v_lshl_add_u64 v[2:3], s[72:73], 0, v[2:3]
	v_lshl_add_u64 v[2:3], v[2:3], 0, s[54:55]
	v_cndmask_b32_e32 v128, v6, v4, vcc
	v_log_f32_e32 v4, v103
	v_sub_f32_e32 v5, v5, v224
	v_cmp_lt_f32_e32 vcc, 0, v102
	v_mov_b32_e32 v166, v1
	v_sub_f32_e32 v4, v4, v224
	v_cndmask_b32_e32 v129, v6, v5, vcc
	s_waitcnt lgkmcnt(12)
	v_log_f32_e32 v5, v104
	v_cmp_lt_f32_e32 vcc, 0, v103
	v_lshl_add_u64 v[2:3], v[2:3], 0, v[166:167]
	v_lshl_add_u64 v[100:101], v[2:3], 0, s[0:1]
	v_cndmask_b32_e32 v130, v6, v4, vcc
	v_log_f32_e32 v4, v105
	v_sub_f32_e32 v5, v5, v224
	v_cmp_lt_f32_e32 vcc, 0, v104
	v_sub_f32_e32 v4, v4, v224
	s_nop 0
	v_cndmask_b32_e32 v131, v6, v5, vcc
	v_cmp_lt_f32_e32 vcc, 0, v105
	s_nop 1
	v_cndmask_b32_e32 v132, v6, v4, vcc
	s_branch .LBB0_1099
.LBB0_1098:
	v_add_f32_e32 v10, v103, v140
	v_add_f32_e32 v11, v102, v139
	v_add_f32_e32 v14, v107, v136
	v_add_f32_e32 v15, v106, v135
	v_add_f32_e32 v90, v111, v125
	v_add_f32_e32 v91, v110, v124
	v_add_f32_e32 v12, v105, v138
	v_add_f32_e32 v13, v104, v137
	v_add_f32_e32 v16, v109, v134
	v_add_f32_e32 v92, v113, v123
	v_add_f32_e32 v10, v10, v189
	v_add_f32_e32 v11, v11, v188
	v_add_f32_e32 v14, v14, v185
	v_add_f32_e32 v15, v15, v184
	v_add_f32_e32 v90, v90, v166
	v_add_f32_e32 v91, v91, v163
	v_add_f32_e32 v17, v108, v133
	v_add_f32_e32 v93, v112, v122
	v_add_f32_e32 v97, v116, v118
	v_add_f32_e32 v12, v12, v187
	v_add_f32_e32 v13, v13, v186
	v_add_f32_e32 v16, v16, v183
	v_add_f32_e32 v92, v92, v162
	v_add_f32_e32 v10, v10, v211
	v_add_f32_e32 v11, v11, v210
	v_add_f32_e32 v14, v14, v203
	v_add_f32_e32 v15, v15, v202
	v_add_f32_e32 v90, v90, v197
	v_add_f32_e32 v91, v91, v196
	v_add_f32_e32 v17, v17, v182
	v_add_f32_e32 v93, v93, v161
	v_add_f32_e32 v97, v97, v157
	v_add_f32_e32 v12, v12, v209
	v_add_f32_e32 v13, v13, v208
	v_add_f32_e32 v16, v16, v201
	v_add_f32_e32 v92, v92, v195
	v_add_f32_e32 v10, v10, v228
	v_add_f32_e32 v11, v11, v227
	v_add_f32_e32 v14, v14, v223
	v_add_f32_e32 v15, v15, v222
	v_add_f32_e32 v90, v90, v219
	v_add_f32_e32 v91, v91, v218
	v_add_f32_e32 v94, v115, v121
	v_add_f32_e32 v95, v114, v120
	v_add_f32_e32 v17, v17, v200
	v_add_f32_e32 v93, v93, v194
	v_add_f32_e32 v97, v97, v190
	v_add_f32_e32 v12, v12, v226
	v_add_f32_e32 v13, v13, v225
	v_add_f32_e32 v16, v16, v221
	v_add_f32_e32 v92, v92, v217
	v_add_f32_e32 v10, v10, v89
	v_add_f32_e32 v11, v11, v88
	v_add_f32_e32 v14, v14, v85
	v_add_f32_e32 v15, v15, v84
	v_add_f32_e32 v9, v90, v9
	v_add_f32_e32 v8, v91, v8
	v_add_f32_e32 v96, v117, v119
	v_add_f32_e32 v94, v94, v160
	v_add_f32_e32 v95, v95, v159
	v_add_f32_e32 v17, v17, v220
	v_add_f32_e32 v93, v93, v216
	v_add_f32_e32 v97, v97, v212
	v_add_f32_e32 v12, v12, v87
	v_add_f32_e32 v13, v13, v86
	v_add_f32_e32 v16, v16, v83
	v_add_f32_e32 v7, v92, v7
	v_add_f32_e32 v10, v11, v10
	v_add_f32_e32 v11, v15, v14
	v_add_f32_e32 v8, v8, v9
	v_add_f32_e32 v96, v96, v158
	v_add_f32_e32 v94, v94, v193
	v_add_f32_e32 v95, v95, v192
	v_add_f32_e32 v17, v17, v82
	v_add_f32_e32 v6, v93, v6
	v_add_f32_e32 v2, v97, v2
	ds_bpermute_b32 v82, v207, v13
	v_add_f32_e32 v10, v12, v10
	v_add_f32_e32 v11, v16, v11
	v_add_f32_e32 v7, v7, v8
	v_add_f32_e32 v96, v96, v191
	v_add_f32_e32 v94, v94, v215
	v_add_f32_e32 v95, v95, v214
	v_fmac_f32_e32 v13, 2.0, v10
	ds_bpermute_b32 v10, v207, v17
	v_fmac_f32_e32 v17, 2.0, v11
	ds_bpermute_b32 v11, v207, v6
	v_fmac_f32_e32 v6, 2.0, v7
	ds_bpermute_b32 v7, v207, v2
	v_add_f32_e32 v96, v96, v213
	v_add_f32_e32 v5, v94, v5
	v_add_f32_e32 v4, v95, v4
	v_add_f32_e32 v3, v96, v3
	v_add_f32_e32 v4, v4, v5
	v_add_f32_e32 v3, v3, v4
	v_fmac_f32_e32 v2, 2.0, v3
	v_add_f32_e32 v3, v167, v13
	s_waitcnt lgkmcnt(3)
	v_add_f32_e32 v4, v13, v82
	v_cndmask_b32_e64 v4, v4, v3, s[2:3]
	s_waitcnt lgkmcnt(0)
	v_cndmask_b32_e64 v3, v7, v11, s[2:3]
	v_cndmask_b32_e64 v8, v11, v10, s[2:3]
	s_mov_b32 s57, s55
	v_cndmask_b32_e64 v5, v10, v82, s[2:3]
	v_add_f32_e32 v6, v6, v8
	v_add_f32_e32 v8, v2, v3
	v_lshl_add_u64 v[2:3], s[56:57], 2, v[100:101]
	s_add_i32 s56, s56, 8
	s_add_i32 s43, s43, 32
	s_waitcnt vmcnt(0)
	v_mov_b64_e32 v[84:85], v[80:81]
	v_mov_b64_e32 v[88:89], v[76:77]
	v_mov_b64_e32 v[92:93], v[72:73]
	v_mov_b64_e32 v[96:97], v[68:69]
	v_mov_b64_e32 v[82:83], v[78:79]
	v_mov_b64_e32 v[86:87], v[74:75]
	v_mov_b64_e32 v[90:91], v[70:71]
	v_mov_b64_e32 v[94:95], v[66:67]
	v_mov_b32_e32 v167, v7
	v_add_f32_e32 v5, v17, v5
	s_cmp_eq_u32 s48, s100
	s_cbranch_scc1 .Lp9_nostore
	global_store_dword v[2:3], v4, off
	global_store_dword v[2:3], v5, off offset:8
	global_store_dword v[2:3], v6, off offset:16
	global_store_dword v[2:3], v8, off offset:24
.Lp9_nostore:
	s_cmp_lg_u32 s99, s48
	s_cbranch_scc0 .LBB0_1123

.LBB0_1133:
	s_cmpk_eq_u32 s55, 0x1800
	s_cbranch_scc1 .Lteam_pull
	v_mov_b32_e32 v3, 0
	s_and_saveexec_b64 s[0:1], s[2:3]
	s_cbranch_execz .LBB0_1137
	s_mov_b64 s[12:13], exec
	v_mbcnt_lo_u32_b32 v3, s12, 0
	v_mbcnt_hi_u32_b32 v3, s13, v3
	v_cmp_eq_u32_e32 vcc, 0, v3
	s_and_saveexec_b64 s[6:7], vcc
	s_cbranch_execz .LBB0_1136
	s_bcnt1_i32_b64 s8, s[12:13]
	s_waitcnt lgkmcnt(12)
	v_mov_b32_e32 v4, s8
	global_atomic_add v4, v2, v4, s[24:25] sc0

.Lteam_have_idx:
	s_cmp_ge_u32 s56, s55
	s_mov_b64 s[0:1], -1
	s_cbranch_scc1 .LBB0_1132
	s_andn2_b64 vcc, exec, s[22:23]
	s_cbranch_vccnz .LBB0_1190
	s_lshr_b32 s60, s56, 1
	s_sub_i32 s0, 0x1ff, s60
	s_lshl_b32 s1, s0, 5
	s_lshl_b32 s0, s0, 1
	s_add_i32 s0, s0, 32
	s_and_b32 s59, s56, 1
	s_ashr_i32 s0, s0, 5
	s_cmp_lt_u32 s1, 0xfffec000
	s_cselect_b32 s57, s0, 0
	s_sub_i32 s0, s1, 31
	s_ashr_i32 s8, s0, 4
	s_lshl_b32 s6, s59, 17
	s_add_u32 s0, s42, s6
	v_or_b32_e32 v3, s1, v185
	s_addc_u32 s1, s43, 0
	s_add_u32 s26, s48, s6
	s_addc_u32 s27, s49, 0
	s_cmp_gt_i32 s57, 0
	s_cselect_b64 s[6:7], -1, 0
	s_add_i32 s62, s57, -1
	s_cmp_eq_u32 s57, 1
	s_cselect_b32 s28, 0, 0x1000
	s_add_u32 s12, s0, s28
	s_addc_u32 s13, s1, 0
	s_add_u32 s64, s26, s28
	s_addc_u32 s65, s27, 0
	s_min_u32 s28, s62, 2
	s_lshl_b32 s28, s28, 12
	s_and_b32 s58, s28, 0x2000
	s_add_u32 s29, s0, s58
	s_addc_u32 s63, s1, 0
	s_and_b32 s66, s28, 0x1000
	s_add_u32 s28, s29, s66
	s_waitcnt lgkmcnt(12)
	v_subrev_u32_e32 v4, 31, v3
	s_addc_u32 s29, s63, 0
	v_lshrrev_b32_e32 v4, 4, v4
	s_add_u32 s58, s26, s58
	v_add_u32_e32 v4, 1, v4
	v_cmp_lt_i32_e32 vcc, 30, v3
	s_addc_u32 s63, s27, 0
	s_add_u32 s66, s58, s66
	v_cndmask_b32_e32 v206, 0, v4, vcc
	v_mov_b64_e32 v[4:5], s[10:11]
	s_addc_u32 s67, s63, 0
	s_sub_i32 s58, s8, 31
	v_mad_i64_i32 v[4:5], s[68:69], v3, s53, v[4:5]
	s_mul_i32 s8, s59, 0x300
	v_lshl_add_u64 v[4:5], v[4:5], 0, s[8:9]
	v_lshlrev_b32_e32 v6, 1, v166
	v_mov_b32_e32 v7, v2
	v_lshl_add_u64 v[210:211], v[4:5], 0, v[6:7]
	v_mov_b64_e32 v[4:5], s[16:17]
	v_mad_i64_i32 v[4:5], s[68:69], v3, s53, v[4:5]
	v_lshl_add_u64 v[4:5], v[4:5], 0, s[8:9]
	v_lshlrev_b32_e32 v6, 1, v168
	v_lshl_add_u64 v[212:213], v[4:5], 0, v[6:7]
	v_mov_b64_e32 v[4:5], s[18:19]
	s_cmpk_lt_u32 s56, 0x3fe
	v_mad_i64_i32 v[4:5], s[68:69], v3, s54, v[4:5]
	s_mul_i32 s8, s59, 0x48
	v_mov_b32_e32 v205, v2
	s_mov_b32 s61, 0
	v_lshl_add_u64 v[214:215], v[4:5], 0, s[8:9]
	v_lshl_add_u64 v[208:209], s[0:1], 0, v[204:205]
	v_lshl_add_u64 v[216:217], s[26:27], 0, v[204:205]
	v_lshl_add_u64 v[218:219], s[12:13], 0, v[204:205]
	v_lshl_add_u64 v[220:221], s[64:65], 0, v[204:205]
	v_lshl_add_u64 v[222:223], s[66:67], 0, v[204:205]
	s_cselect_b32 s58, s58, 0xffffffe0
	s_branch .LBB0_1142

.Lteam_pull:
	s_mov_b64 s[12:13], exec
	s_mov_b64 exec, 1
	v_mov_b32_e32 v3, 0x1d500
.Lteam_retry:
	v_mov_b32_e32 v4, 1
	ds_add_rtn_u32 v4, v3, v4
	s_waitcnt lgkmcnt(0)
	v_readfirstlane_b32 s0, v4
	s_and_b32 s1, s0, 15
	s_lshr_b32 s0, s0, 4
	s_cmp_lt_u32 s1, 6
	s_cbranch_scc1 .Lteam_got
	s_cmp_eq_u32 s1, 6
	s_cbranch_scc1 .Lteam_refill
.Lteam_spin:
	s_sleep 2
	ds_read_b32 v4, v3
	s_waitcnt lgkmcnt(0)
	v_readfirstlane_b32 s0, v4
	s_and_b32 s1, s0, 15
	s_cmp_lt_u32 s1, 6
	s_cbranch_scc1 .Lteam_retry
	s_branch .Lteam_spin
.Lteam_refill:
	v_mov_b32_e32 v4, 6
	global_atomic_add v4, v2, v4, s[24:25] sc0
	s_waitcnt vmcnt(0)
	v_lshlrev_b32_e32 v4, 4, v4
	ds_write_b32 v3, v4
	s_waitcnt lgkmcnt(0)
	s_branch .Lteam_retry
.Lteam_got:
	s_add_i32 s56, s0, s1
	s_mov_b64 exec, s[12:13]
	s_branch .Lteam_have_idx

.LBB0_1268:
	s_or_b64 exec, exec, s[0:1]
	s_lshl_b32 s0, s53, 6
	s_add_i32 s1, s53, -2
	v_cmp_lt_i32_e32 vcc, s1, v223
	s_add_i32 s18, s34, s0
	s_or_b64 s[30:31], s[4:5], vcc
	v_cmp_gt_i32_e32 vcc, s1, v223
	v_cmp_lt_i32_e64 s[8:9], s1, v224
	v_cmp_lt_i32_e64 s[10:11], s1, v225
	s_lshl_b64 s[0:1], s[18:19], 11
	s_bitcmp1_b32 s12, 0
	s_cselect_b64 s[12:13], -1, 0
	s_xor_b64 s[12:13], s[12:13], -1
	v_cndmask_b32_e64 v2, 0, 1, s[12:13]
	v_lshlrev_b32_e32 v2, 10, v2
	s_waitcnt vmcnt(47)
	v_or_b32_e32 v4, s0, v2
	v_mov_b32_e32 v5, s1
	v_lshl_add_u64 v[4:5], v[208:209], 0, v[4:5]
	s_mov_b32 s18, 0
	global_load_dwordx4 v[12:15], v[4:5], off
	s_branch .LBB0_1270

.LBB0_1270:
	s_waitcnt vmcnt(0)
	v_mov_b64_e32 v[6:7], v[12:13]
	v_mov_b64_e32 v[8:9], v[14:15]
	v_lshl_add_u64 v[16:17], v[4:5], 0, s[26:27]
	global_load_dwordx4 v[12:15], v[16:17], off
	s_add_i32 s0, s46, s18
	s_lshl_b32 s55, 1, s0
	v_add_u32_e32 v2, 1, v6
	v_add_u32_e32 v6, 1, v7
	v_add_u32_e32 v7, 1, v8
	v_add_u32_e32 v8, 1, v9
	v_cndmask_b32_e64 v7, v7, 0, s[8:9]
	v_cndmask_b32_e64 v8, v8, 0, s[10:11]
	v_cndmask_b32_e64 v2, v2, 0, s[30:31]
	v_cndmask_b32_e32 v6, 0, v6, vcc
	v_max_u32_e32 v9, v7, v8
	v_max3_u32 v9, v2, v6, v9
	s_nop 1
	v_max_u32_dpp v10, v9, v9 row_shr:1 row_mask:0xf bank_mask:0xf bound_ctrl:1
	s_nop 1
	v_max_u32_dpp v10, v10, v10 row_shr:2 row_mask:0xf bank_mask:0xf bound_ctrl:1
	s_nop 1
	v_max_u32_dpp v10, v10, v10 row_shr:4 row_mask:0xf bank_mask:0xf bound_ctrl:1
	s_nop 1
	v_max_u32_dpp v10, v10, v10 row_shr:8 row_mask:0xf bank_mask:0xf bound_ctrl:1
	s_nop 1
	v_max_u32_dpp v10, v10, v10 row_bcast:15 row_mask:0xa bank_mask:0xf
	s_nop 1
	v_max_u32_dpp v10, v10, v10 row_bcast:31 row_mask:0xc bank_mask:0xf
	s_nop 0
	v_readlane_b32 s14, v10, 63
	s_nop 1
	v_cmp_eq_u32_e64 s[0:1], s14, v9
	s_cmp_lg_u64 s[0:1], 0
	s_ff1_i32_b64 s0, s[0:1]
	s_cselect_b64 s[12:13], -1, 0
	v_cmp_eq_u32_e64 s[0:1], s0, v199
	s_and_b64 s[0:1], s[12:13], s[0:1]
	s_and_saveexec_b64 s[12:13], s[0:1]
	s_cbranch_execz .LBB0_1272
	v_cmp_eq_u32_e64 s[0:1], s14, v7
	v_mov_b32_e32 v11, s55
	s_nop 0
	v_cndmask_b32_e64 v9, 3, 2, s[0:1]
	v_cmp_eq_u32_e64 s[0:1], s14, v6
	v_cmp_ne_u32_e64 s[14:15], s14, v2
	s_nop 0
	v_cndmask_b32_e64 v9, v9, 1, s[0:1]
	v_cndmask_b32_e64 v9, 0, v9, s[14:15]
	v_or_b32_e32 v10, v9, v223
	s_and_b64 s[0:1], s[14:15], s[0:1]
	v_lshl_add_u32 v10, v10, 3, s35
	v_cndmask_b32_e64 v6, v6, 0, s[0:1]
	v_cmp_ne_u32_e64 s[0:1], 2, v9
	ds_or_b32 v10, v11
	v_cndmask_b32_e64 v2, 0, v2, s[14:15]
	v_cndmask_b32_e64 v7, 0, v7, s[0:1]
	v_cmp_ne_u32_e64 s[0:1], 3, v9
	s_nop 1
	v_cndmask_b32_e64 v8, 0, v8, s[0:1]
	v_max_u32_e32 v9, v7, v8
	v_max3_u32 v9, v2, v6, v9

.LBB0_1296:
	s_waitcnt vmcnt(0)
	s_mov_b64 s[0:1], 0
